# pool unit: the nine serialized load-wait-LDS-write rounds of the staging (weights + p_in rows) replaced by nine loads in flight and one wait
# speedup vs baseline: 1.0109x; 1.0013x over previous
.Lp2_again:
	s_mov_b64 s[26:27], s[96:97]
	s_load_dwordx2 s[60:61], s[26:27], 0xa8
	v_mov_b32_e32 v0, v224
	s_load_dwordx8 s[40:47], s[26:27], 0x20
	v_xor_b32_e32 v7, 2, v230
	s_waitcnt lgkmcnt(0)
	s_add_u32 s28, s60, 0x5000000
	s_addc_u32 s29, s61, 0
	s_add_u32 s50, s60, 0x8000000
	s_addc_u32 s51, s61, 0
	s_cmp_eq_u32 s98, 1
	s_cbranch_scc1 .LBB0_441
	s_lshl_b32 s8, s86, 6
	v_and_or_b32 v0, v0, 63, s8
	v_lshlrev_b64 v[2:3], 2, v[0:1]
	v_lshl_add_u64 v[4:5], s[40:41], 0, v[2:3]
	global_load_dword v0, v[4:5], off
	v_lshl_add_u64 v[4:5], s[42:43], 0, v[2:3]
	global_load_dword v6, v[4:5], off
	v_lshl_add_u64 v[4:5], s[44:45], 0, v[2:3]
	v_lshl_add_u64 v[2:3], s[46:47], 0, v[2:3]
	global_load_dword v4, v[4:5], off
	v_xor_b32_e32 v5, 1, v230
	global_load_dword v2, v[2:3], off
	v_and_b32_e32 v3, 64, v230
	v_add_u32_e32 v3, 64, v3
	v_cmp_lt_i32_e32 vcc, v5, v3
	v_xor_b32_e32 v8, 4, v230
	v_xor_b32_e32 v9, 8, v230
	v_cndmask_b32_e32 v5, v230, v5, vcc
	v_lshlrev_b32_e32 v5, 2, v5
	v_cmp_lt_i32_e32 vcc, v7, v3
	v_xor_b32_e32 v10, 16, v230
	v_xor_b32_e32 v11, 32, v230
	v_cndmask_b32_e32 v7, v230, v7, vcc
	v_lshlrev_b32_e32 v7, 2, v7
	v_cmp_lt_i32_e32 vcc, v8, v3
	v_readlane_b32 s8, v241, 23
	v_readlane_b32 s9, v241, 24
	s_waitcnt vmcnt(0)
	v_mul_f32_e32 v12, v0, v6
	ds_bpermute_b32 v12, v5, v12
	v_mul_f32_e32 v13, v4, v2
	ds_bpermute_b32 v5, v5, v13
	s_waitcnt lgkmcnt(1)
	v_fmac_f32_e32 v12, v0, v6
	ds_bpermute_b32 v0, v7, v12
	s_waitcnt lgkmcnt(1)
	v_fmac_f32_e32 v5, v4, v2
	ds_bpermute_b32 v2, v7, v5
	v_cndmask_b32_e32 v4, v230, v8, vcc
	v_lshlrev_b32_e32 v4, 2, v4
	s_waitcnt lgkmcnt(1)
	v_add_f32_e32 v0, v12, v0
	v_cmp_lt_i32_e32 vcc, v9, v3
	s_waitcnt lgkmcnt(0)
	v_add_f32_e32 v2, v5, v2
	ds_bpermute_b32 v5, v4, v0
	ds_bpermute_b32 v4, v4, v2
	v_cndmask_b32_e32 v6, v230, v9, vcc
	v_lshlrev_b32_e32 v6, 2, v6
	v_cmp_lt_i32_e32 vcc, v10, v3
	s_waitcnt lgkmcnt(1)
	v_add_f32_e32 v0, v0, v5
	s_waitcnt lgkmcnt(0)
	v_add_f32_e32 v2, v2, v4
	ds_bpermute_b32 v4, v6, v0
	ds_bpermute_b32 v5, v6, v2
	v_cndmask_b32_e32 v6, v230, v10, vcc
	v_lshlrev_b32_e32 v148, 2, v6
	v_cmp_lt_i32_e32 vcc, v11, v3
	s_waitcnt lgkmcnt(1)
	v_add_f32_e32 v0, v0, v4
	s_waitcnt lgkmcnt(0)
	v_add_f32_e32 v2, v2, v5
	ds_bpermute_b32 v4, v148, v0
	ds_bpermute_b32 v5, v148, v2
	v_cndmask_b32_e32 v3, v230, v11, vcc
	v_lshlrev_b32_e32 v149, 2, v3
	s_andn2_b64 vcc, exec, s[8:9]
	s_waitcnt lgkmcnt(1)
	v_add_f32_e32 v0, v0, v4
	s_waitcnt lgkmcnt(0)
	v_add_f32_e32 v2, v2, v5
	ds_bpermute_b32 v3, v149, v0
	ds_bpermute_b32 v4, v149, v2
	s_cbranch_vccnz .LBB0_441
	s_cmp_eq_u32 s98, 1
	s_cbranch_scc1 .LBB0_441
	s_waitcnt lgkmcnt(1)
	v_add_f32_e32 v0, v0, v3
	v_cvt_f32_u32_e32 v3, s86
	s_waitcnt lgkmcnt(0)
	v_add_f32_e32 v2, v2, v4
	s_load_dwordx2 s[8:9], s[26:27], 0x40
	v_mul_f32_e32 v0, 0x3fb8aa3b, v0
	v_mul_f32_e32 v3, 0xbe99999a, v3
	v_mul_f32_e32 v3, 0x3fb8aa3b, v3
	v_mul_f32_e32 v2, 0x3fb8aa3b, v2
	v_exp_f32_e32 v3, v3
	v_exp_f32_e32 v0, v0
	v_exp_f32_e32 v2, v2
	s_add_u32 s40, s60, 0xd000000
	s_addc_u32 s41, s61, 0
	s_lshl_b32 s30, s86, 7
	s_lshl_b64 s[38:39], s[30:31], 2
	v_fmamk_f32 v3, v3, 0xbf19999a, v226
	v_sub_f32_e32 v0, v0, v2
	s_waitcnt lgkmcnt(0)
	s_add_u32 s42, s8, s38
	v_readlane_b32 s13, v241, 45
	v_add_f32_e32 v150, v3, v0
	v_sub_f32_e32 v151, 1.0, v3
	s_addc_u32 s43, s9, s39
	s_mov_b32 s8, s13
	v_readlane_b32 s9, v241, 46
	s_branch .LBB0_393

.LBB0_448:
	s_and_b64 vcc, exec, s[38:39]
	s_cbranch_vccz .LBB0_443
	s_load_dwordx4 s[44:47], s[26:27], 0x50
	s_lshl_b64 s[38:39], s[40:41], 2
	v_mov_b32_e32 v47, v224
	s_waitcnt lgkmcnt(0)
	s_add_u32 s44, s44, s38
	s_addc_u32 s45, s45, s39
	s_add_u32 s38, s46, s38
	v_readfirstlane_b32 s30, v47
	s_addc_u32 s39, s47, s39
	v_bfe_u32 v58, v47, 4, 2
	s_lshr_b32 s46, s30, 1
	v_lshrrev_b32_e32 v2, 2, v47
	s_lshl_b32 s61, s55, 7
	s_lshl_b32 s60, s56, 7
	s_ashr_i32 s56, s30, 2
	s_and_b32 s57, s46, 0x60
	v_and_b32_e32 v18, 8, v2
	v_lshl_or_b32 v2, v58, 2, s61
	s_andn2_b32 s56, s56, 63
	v_and_b32_e32 v0, 16, v47
	v_or_b32_e32 v2, s57, v2
	v_and_b32_e32 v59, 15, v47
	s_add_i32 s30, s56, s60
	v_lshlrev_b32_e32 v2, 2, v2
	v_or3_b32 v0, v18, v0, s57
	v_or_b32_e32 v34, s30, v59
	v_mov_b64_e32 v[18:19], s[28:29]
	global_load_dwordx4 v[14:17], v2, s[44:45]
	global_load_dwordx4 v[10:13], v2, s[38:39]
	global_load_dwordx4 v[6:9], v2, s[44:45] offset:64
	s_nop 0
	global_load_dwordx4 v[2:5], v2, s[38:39] offset:64
	v_mad_i64_i32 v[20:21], s[38:39], v34, s23, v[18:19]
	s_lshl_b32 s30, s55, 8
	v_lshl_add_u64 v[20:21], v[20:21], 0, s[30:31]
	v_lshlrev_b32_e32 v0, 1, v0
	v_lshl_add_u64 v[44:45], v[20:21], 0, v[0:1]
	v_or_b32_e32 v20, 16, v34
	v_mad_i64_i32 v[20:21], s[38:39], v20, s23, v[18:19]
	v_lshl_add_u64 v[20:21], v[20:21], 0, s[30:31]
	v_lshl_add_u64 v[42:43], v[20:21], 0, v[0:1]
	v_or_b32_e32 v20, 32, v34
	v_mad_i64_i32 v[20:21], s[38:39], v20, s23, v[18:19]
	v_lshl_add_u64 v[20:21], v[20:21], 0, s[30:31]
	v_lshl_add_u64 v[40:41], v[20:21], 0, v[0:1]
	v_or_b32_e32 v20, 48, v34
	v_mad_i64_i32 v[18:19], s[38:39], v20, s23, v[18:19]
	v_lshl_add_u64 v[18:19], v[18:19], 0, s[30:31]
	s_lshl_b32 s30, s55, 15
	s_add_u32 s38, s8, s30
	v_ashrrev_i32_e32 v56, 4, v47
	v_lshl_add_u64 v[38:39], v[18:19], 0, v[0:1]
	s_addc_u32 s39, s9, 0
	v_lshlrev_b32_e32 v0, 4, v59
	v_lshlrev_b32_e32 v34, 7, v56
	v_lshl_add_u64 v[60:61], s[38:39], 0, v[0:1]
	v_ashrrev_i32_e32 v35, 31, v34
	v_lshl_add_u64 v[34:35], v[34:35], 1, v[60:61]
	global_load_dwordx4 v[104:107], v[34:35], off
	global_load_dwordx4 v[30:33], v[44:45], off offset:1024
	global_load_dwordx4 v[26:29], v[42:43], off offset:1024
	global_load_dwordx4 v[22:25], v[40:41], off offset:1024
	global_load_dwordx4 v[18:21], v[38:39], off offset:1024
	v_add_u32_e32 v34, 0x200, v47
	v_ashrrev_i32_e32 v54, 4, v34
	v_lshlrev_b32_e32 v34, 7, v54
	v_ashrrev_i32_e32 v35, 31, v34
	v_lshl_add_u64 v[34:35], v[34:35], 1, v[60:61]
	global_load_dwordx4 v[108:111], v[34:35], off
	v_add_u32_e32 v34, 0x400, v47
	v_ashrrev_i32_e32 v52, 4, v34
	v_lshlrev_b32_e32 v34, 7, v52
	v_ashrrev_i32_e32 v35, 31, v34
	v_lshl_add_u64 v[34:35], v[34:35], 1, v[60:61]
	global_load_dwordx4 v[112:115], v[34:35], off
	v_add_u32_e32 v34, 0x600, v47
	v_ashrrev_i32_e32 v49, 4, v34
	v_lshlrev_b32_e32 v34, 7, v49
	v_ashrrev_i32_e32 v35, 31, v34
	v_lshl_add_u64 v[34:35], v[34:35], 1, v[60:61]
	global_load_dwordx4 v[116:119], v[34:35], off
	v_add_u32_e32 v34, 0x800, v47
	v_ashrrev_i32_e32 v57, 4, v34
	s_and_b32 s30, s25, 60
	s_cmp_eq_u32 s30, 0
	s_cselect_b64 s[38:39], -1, 0
	s_xor_b64 s[46:47], s[38:39], -1
	s_add_i32 s62, 0, 0x11000
	s_add_i32 s63, s60, -15
	s_lshl_b32 s30, s61, 1
	v_lshlrev_b32_e32 v0, 4, v59
	v_mov_b32_e32 v120, 0
	v_mov_b32_e32 v121, 0
	v_mov_b32_e32 v122, 0
	v_mov_b32_e32 v123, 0
	v_cmp_gt_i32_e32 vcc, 0x8f, v56
	v_cmp_lt_i32_e64 s[64:65], 14, v56
	v_add_u32_e32 v36, s63, v56
	v_mov_b64_e32 v[34:35], s[50:51]
	s_or_b64 s[64:65], s[46:47], s[64:65]
	s_and_b64 s[64:65], s[64:65], vcc
	s_and_saveexec_b64 s[44:45], s[64:65]
	v_mad_i64_i32 v[34:35], s[64:65], v36, s21, v[34:35]
	v_lshl_add_u64 v[34:35], v[34:35], 0, s[30:31]
	v_lshl_add_u64 v[34:35], v[34:35], 0, v[0:1]
	global_load_dwordx4 v[120:123], v[34:35], off offset:2048
	s_or_b64 exec, exec, s[44:45]
	v_mov_b32_e32 v124, 0
	v_mov_b32_e32 v125, 0
	v_mov_b32_e32 v126, 0
	v_mov_b32_e32 v127, 0
	v_cmp_gt_i32_e32 vcc, 0x8f, v54
	v_cmp_lt_i32_e64 s[64:65], 14, v54
	v_add_u32_e32 v36, s63, v54
	v_mov_b64_e32 v[34:35], s[50:51]
	s_or_b64 s[64:65], s[46:47], s[64:65]
	s_and_b64 s[64:65], s[64:65], vcc
	s_and_saveexec_b64 s[44:45], s[64:65]
	v_mad_i64_i32 v[34:35], s[64:65], v36, s21, v[34:35]
	v_lshl_add_u64 v[34:35], v[34:35], 0, s[30:31]
	v_lshl_add_u64 v[34:35], v[34:35], 0, v[0:1]
	global_load_dwordx4 v[124:127], v[34:35], off offset:2048
	s_or_b64 exec, exec, s[44:45]
	v_mov_b32_e32 v128, 0
	v_mov_b32_e32 v129, 0
	v_mov_b32_e32 v130, 0
	v_mov_b32_e32 v131, 0
	v_cmp_gt_i32_e32 vcc, 0x8f, v52
	v_cmp_lt_i32_e64 s[64:65], 14, v52
	v_add_u32_e32 v36, s63, v52
	v_mov_b64_e32 v[34:35], s[50:51]
	s_or_b64 s[64:65], s[46:47], s[64:65]
	s_and_b64 s[64:65], s[64:65], vcc
	s_and_saveexec_b64 s[44:45], s[64:65]
	v_mad_i64_i32 v[34:35], s[64:65], v36, s21, v[34:35]
	v_lshl_add_u64 v[34:35], v[34:35], 0, s[30:31]
	v_lshl_add_u64 v[34:35], v[34:35], 0, v[0:1]
	global_load_dwordx4 v[128:131], v[34:35], off offset:2048
	s_or_b64 exec, exec, s[44:45]
	v_mov_b32_e32 v132, 0
	v_mov_b32_e32 v133, 0
	v_mov_b32_e32 v134, 0
	v_mov_b32_e32 v135, 0
	v_cmp_gt_i32_e32 vcc, 0x8f, v49
	v_cmp_lt_i32_e64 s[64:65], 14, v49
	v_add_u32_e32 v36, s63, v49
	v_mov_b64_e32 v[34:35], s[50:51]
	s_or_b64 s[64:65], s[46:47], s[64:65]
	s_and_b64 s[64:65], s[64:65], vcc
	s_and_saveexec_b64 s[44:45], s[64:65]
	v_mad_i64_i32 v[34:35], s[64:65], v36, s21, v[34:35]
	v_lshl_add_u64 v[34:35], v[34:35], 0, s[30:31]
	v_lshl_add_u64 v[34:35], v[34:35], 0, v[0:1]
	global_load_dwordx4 v[132:135], v[34:35], off offset:2048
	s_or_b64 exec, exec, s[44:45]
	v_mov_b32_e32 v136, 0
	v_mov_b32_e32 v137, 0
	v_mov_b32_e32 v138, 0
	v_mov_b32_e32 v139, 0
	v_cmp_gt_i32_e32 vcc, 0x8f, v57
	v_cmp_lt_i32_e64 s[64:65], 14, v57
	v_add_u32_e32 v36, s63, v57
	v_mov_b64_e32 v[34:35], s[50:51]
	s_or_b64 s[64:65], s[46:47], s[64:65]
	s_and_b64 s[64:65], s[64:65], vcc
	s_and_saveexec_b64 s[44:45], s[64:65]
	v_mad_i64_i32 v[34:35], s[64:65], v36, s21, v[34:35]
	v_lshl_add_u64 v[34:35], v[34:35], 0, s[30:31]
	v_lshl_add_u64 v[34:35], v[34:35], 0, v[0:1]
	global_load_dwordx4 v[136:139], v[34:35], off offset:2048
	s_or_b64 exec, exec, s[44:45]
	v_mul_lo_u32 v55, v56, s90
	v_mul_lo_u32 v53, v54, s90
	v_mul_lo_u32 v50, v52, s90
	v_mul_lo_u32 v51, v49, s90
	v_mul_lo_u32 v48, v57, s90
	v_add_u32_e32 v46, s62, v0
	s_waitcnt vmcnt(0)
	v_add_u32_e32 v34, v0, v55
	ds_write_b128 v34, v[104:107] offset:34816
	v_add_u32_e32 v34, v0, v53
	ds_write_b128 v34, v[108:111] offset:34816
	v_add_u32_e32 v34, v0, v50
	ds_write_b128 v34, v[112:115] offset:34816
	v_add_u32_e32 v34, v0, v51
	ds_write_b128 v34, v[116:119] offset:34816
	v_cmp_gt_i32_e32 vcc, 0x8f, v56
	v_add_u32_e32 v34, v46, v55
	s_and_saveexec_b64 s[44:45], vcc
	ds_write_b128 v34, v[120:123]
	s_or_b64 exec, exec, s[44:45]
	v_cmp_gt_i32_e32 vcc, 0x8f, v54
	v_add_u32_e32 v34, v46, v53
	s_and_saveexec_b64 s[44:45], vcc
	ds_write_b128 v34, v[124:127]
	s_or_b64 exec, exec, s[44:45]
	v_cmp_gt_i32_e32 vcc, 0x8f, v52
	v_add_u32_e32 v34, v46, v50
	s_and_saveexec_b64 s[44:45], vcc
	ds_write_b128 v34, v[128:131]
	s_or_b64 exec, exec, s[44:45]
	v_cmp_gt_i32_e32 vcc, 0x8f, v49
	v_add_u32_e32 v34, v46, v51
	s_and_saveexec_b64 s[44:45], vcc
	ds_write_b128 v34, v[132:135]
	s_or_b64 exec, exec, s[44:45]
	v_cmp_gt_i32_e32 vcc, 0x8f, v57
	v_add_u32_e32 v34, v46, v48
	s_and_saveexec_b64 s[44:45], vcc
	ds_write_b128 v34, v[136:139]
	s_or_b64 exec, exec, s[44:45]
